# GEMM K-loop: LDS-DMA loads use scalar base + 32-bit lane offset (14 64-bit VALU adds per iteration removed), LDS read bases precomputed per unit
# speedup vs baseline: 1.0157x; 1.0142x over previous
.LBB0_168:
	s_add_u32 s80, s80, 0x80
	s_addc_u32 s81, s81, 0
	s_add_u32 vcc_lo, s34, 0x100
	v_add_u32_e32 v206, 0x10000, v234
	v_add_u32_e32 v207, 0x14000, v234
	v_add_u32_e32 v208, 0x18000, v234
	v_add_u32_e32 v209, 0x1c000, v234
	v_mov_b32_e32 v2, 0
	s_addc_u32 vcc_hi, s35, 0
	s_mov_b32 s34, 0
	v_mov_b32_e32 v3, v2
	v_mov_b32_e32 v4, v2
	v_mov_b32_e32 v5, v2
	v_mov_b32_e32 v6, v2
	v_mov_b32_e32 v7, v2
	v_mov_b32_e32 v8, v2
	v_mov_b32_e32 v9, v2
	v_mov_b32_e32 v18, v2
	v_mov_b32_e32 v19, v2
	v_mov_b32_e32 v20, v2
	v_mov_b32_e32 v21, v2
	v_mov_b32_e32 v22, v2
	v_mov_b32_e32 v23, v2
	v_mov_b32_e32 v24, v2
	v_mov_b32_e32 v25, v2
	v_mov_b32_e32 v34, v2
	v_mov_b32_e32 v35, v2
	v_mov_b32_e32 v36, v2
	v_mov_b32_e32 v37, v2
	v_mov_b32_e32 v38, v2
	v_mov_b32_e32 v39, v2
	v_mov_b32_e32 v40, v2
	v_mov_b32_e32 v41, v2
	v_mov_b32_e32 v50, v2
	v_mov_b32_e32 v51, v2
	v_mov_b32_e32 v52, v2
	v_mov_b32_e32 v53, v2
	v_mov_b32_e32 v54, v2
	v_mov_b32_e32 v55, v2
	v_mov_b32_e32 v56, v2
	v_mov_b32_e32 v57, v2
	v_mov_b32_e32 v10, v2
	v_mov_b32_e32 v11, v2
	v_mov_b32_e32 v12, v2
	v_mov_b32_e32 v13, v2
	v_mov_b32_e32 v14, v2
	v_mov_b32_e32 v15, v2
	v_mov_b32_e32 v16, v2
	v_mov_b32_e32 v17, v2
	v_mov_b32_e32 v26, v2
	v_mov_b32_e32 v27, v2
	v_mov_b32_e32 v28, v2
	v_mov_b32_e32 v29, v2
	v_mov_b32_e32 v30, v2
	v_mov_b32_e32 v31, v2
	v_mov_b32_e32 v32, v2
	v_mov_b32_e32 v33, v2
	v_mov_b32_e32 v42, v2
	v_mov_b32_e32 v43, v2
	v_mov_b32_e32 v44, v2
	v_mov_b32_e32 v45, v2
	v_mov_b32_e32 v46, v2
	v_mov_b32_e32 v47, v2
	v_mov_b32_e32 v48, v2
	v_mov_b32_e32 v49, v2
	v_mov_b32_e32 v58, v2
	v_mov_b32_e32 v59, v2
	v_mov_b32_e32 v60, v2
	v_mov_b32_e32 v61, v2
	v_mov_b32_e32 v62, v2
	v_mov_b32_e32 v63, v2
	v_mov_b32_e32 v64, v2
	v_mov_b32_e32 v65, v2
	s_waitcnt vmcnt(0)
	v_mov_b32_e32 v66, v2
	v_mov_b32_e32 v67, v2
	v_mov_b32_e32 v68, v2
	v_mov_b32_e32 v69, v2
	v_mov_b32_e32 v70, v2
	v_mov_b32_e32 v71, v2
	v_mov_b32_e32 v72, v2
	v_mov_b32_e32 v73, v2
	v_mov_b32_e32 v82, v2
	v_mov_b32_e32 v83, v2
	v_mov_b32_e32 v84, v2
	v_mov_b32_e32 v85, v2
	v_mov_b32_e32 v86, v2
	v_mov_b32_e32 v87, v2
	v_mov_b32_e32 v88, v2
	v_mov_b32_e32 v89, v2
	v_mov_b32_e32 v98, v2
	v_mov_b32_e32 v99, v2
	v_mov_b32_e32 v100, v2
	v_mov_b32_e32 v101, v2
	v_mov_b32_e32 v106, v2
	v_mov_b32_e32 v107, v2
	v_mov_b32_e32 v108, v2
	v_mov_b32_e32 v109, v2
	v_mov_b32_e32 v110, v2
	v_mov_b32_e32 v111, v2
	v_mov_b32_e32 v112, v2
	v_mov_b32_e32 v113, v2
	v_mov_b32_e32 v114, v2
	v_mov_b32_e32 v115, v2
	v_mov_b32_e32 v116, v2
	v_mov_b32_e32 v117, v2
	v_mov_b32_e32 v74, v2
	v_mov_b32_e32 v75, v2
	v_mov_b32_e32 v76, v2
	v_mov_b32_e32 v77, v2
	v_mov_b32_e32 v78, v2
	v_mov_b32_e32 v79, v2
	v_mov_b32_e32 v80, v2
	v_mov_b32_e32 v81, v2
	v_mov_b32_e32 v90, v2
	v_mov_b32_e32 v91, v2
	v_mov_b32_e32 v92, v2
	v_mov_b32_e32 v93, v2
	v_mov_b32_e32 v94, v2
	v_mov_b32_e32 v95, v2
	v_mov_b32_e32 v96, v2
	v_mov_b32_e32 v97, v2
	v_mov_b32_e32 v102, v2
	v_mov_b32_e32 v103, v2
	v_mov_b32_e32 v104, v2
	v_mov_b32_e32 v105, v2
	v_mov_b32_e32 v118, v2
	v_mov_b32_e32 v119, v2
	v_mov_b32_e32 v120, v2
	v_mov_b32_e32 v121, v2
	v_mov_b32_e32 v122, v2
	v_mov_b32_e32 v123, v2
	v_mov_b32_e32 v124, v2
	v_mov_b32_e32 v125, v2
	v_mov_b32_e32 v126, v2
	v_mov_b32_e32 v127, v2
	v_mov_b32_e32 v128, v2
	v_mov_b32_e32 v129, v2
.LBB0_169:
	s_add_i32 s0, s34, 2
	s_add_u32 s1, s80, 0x80
	s_addc_u32 s35, s81, 0
	s_add_i32 s47, 0, 0x10000
	s_cmp_eq_u32 s68, s34
	s_cselect_b32 s35, s43, s35
	s_cselect_b32 s34, s42, s1
	s_cselect_b32 s67, s87, vcc_hi
	s_cselect_b32 s66, s86, vcc_lo
	s_add_i32 s1, 0, 0x14000
	s_waitcnt lgkmcnt(0)
	ds_read_b128 v[130:133], v206
	ds_read_b128 v[134:137], v206 offset:1024
	ds_read_b128 v[138:141], v206 offset:2048
	ds_read_b128 v[142:145], v206 offset:3072
	ds_read_b128 v[146:149], v207
	ds_read_b128 v[150:153], v207 offset:1024
	ds_read_b128 v[154:157], v207 offset:2048
	ds_read_b128 v[158:161], v207 offset:3072
	s_add_i32 m0, s90, 0xc000
	ds_read_b128 v[162:165], v238
	ds_read_b128 v[166:169], v238 offset:1024
	ds_read_b128 v[170:173], v238 offset:2048
	ds_read_b128 v[174:177], v238 offset:3072
	ds_read_b128 v[178:181], v238 offset:4096
	ds_read_b128 v[182:185], v238 offset:5120
	ds_read_b128 v[198:201], v238 offset:6144
	ds_read_b128 v[202:205], v238 offset:7168
	global_load_lds_dwordx4 v194, s[80:81]
	s_add_i32 m0, s90, 0xe000
	s_nop 0
	global_load_lds_dwordx4 v196, s[80:81]
	s_waitcnt vmcnt(8)
	s_waitcnt lgkmcnt(0)
	s_barrier
	s_setprio 1
	s_waitcnt lgkmcnt(0)
	v_mfma_f32_16x16x32_bf16 v[126:129], v[130:133], v[162:165], v[126:129]
	v_mfma_f32_16x16x32_bf16 v[122:125], v[138:141], v[162:165], v[122:125]
	v_mfma_f32_16x16x32_bf16 v[118:121], v[130:133], v[170:173], v[118:121]
	v_mfma_f32_16x16x32_bf16 v[102:105], v[138:141], v[170:173], v[102:105]
	v_mfma_f32_16x16x32_bf16 v[94:97], v[130:133], v[178:181], v[94:97]
	v_mfma_f32_16x16x32_bf16 v[90:93], v[138:141], v[178:181], v[90:93]
	v_mfma_f32_16x16x32_bf16 v[78:81], v[130:133], v[198:201], v[78:81]
	v_mfma_f32_16x16x32_bf16 v[74:77], v[138:141], v[198:201], v[74:77]
	v_mfma_f32_16x16x32_bf16 v[126:129], v[134:137], v[166:169], v[126:129]
	v_mfma_f32_16x16x32_bf16 v[122:125], v[142:145], v[166:169], v[122:125]
	v_mfma_f32_16x16x32_bf16 v[118:121], v[134:137], v[174:177], v[118:121]
	v_mfma_f32_16x16x32_bf16 v[102:105], v[142:145], v[174:177], v[102:105]
	v_mfma_f32_16x16x32_bf16 v[94:97], v[134:137], v[182:185], v[94:97]
	v_mfma_f32_16x16x32_bf16 v[90:93], v[142:145], v[182:185], v[90:93]
	v_mfma_f32_16x16x32_bf16 v[78:81], v[134:137], v[202:205], v[78:81]
	v_mfma_f32_16x16x32_bf16 v[74:77], v[142:145], v[202:205], v[74:77]
	s_setprio 0
	s_setprio 1
	v_mfma_f32_16x16x32_bf16 v[114:117], v[146:149], v[162:165], v[114:117]
	v_mfma_f32_16x16x32_bf16 v[110:113], v[154:157], v[162:165], v[110:113]
	v_mfma_f32_16x16x32_bf16 v[106:109], v[146:149], v[170:173], v[106:109]
	v_mfma_f32_16x16x32_bf16 v[98:101], v[154:157], v[170:173], v[98:101]
	v_mfma_f32_16x16x32_bf16 v[86:89], v[146:149], v[178:181], v[86:89]
	v_mfma_f32_16x16x32_bf16 v[82:85], v[154:157], v[178:181], v[82:85]
	v_mfma_f32_16x16x32_bf16 v[70:73], v[146:149], v[198:201], v[70:73]
	v_mfma_f32_16x16x32_bf16 v[66:69], v[154:157], v[198:201], v[66:69]
	v_mfma_f32_16x16x32_bf16 v[114:117], v[150:153], v[166:169], v[114:117]
	v_mfma_f32_16x16x32_bf16 v[110:113], v[158:161], v[166:169], v[110:113]
	v_mfma_f32_16x16x32_bf16 v[106:109], v[150:153], v[174:177], v[106:109]
	v_mfma_f32_16x16x32_bf16 v[98:101], v[158:161], v[174:177], v[98:101]
	v_mfma_f32_16x16x32_bf16 v[86:89], v[150:153], v[182:185], v[86:89]
	v_mfma_f32_16x16x32_bf16 v[82:85], v[158:161], v[182:185], v[82:85]
	v_mfma_f32_16x16x32_bf16 v[70:73], v[150:153], v[202:205], v[70:73]
	v_mfma_f32_16x16x32_bf16 v[66:69], v[158:161], v[202:205], v[66:69]
	s_setprio 0
	s_barrier
	s_add_i32 s47, s47, s57
	s_mov_b32 m0, s47
	ds_read_b128 v[162:165], v238 offset:16384
	ds_read_b128 v[166:169], v238 offset:17408
	ds_read_b128 v[170:173], v238 offset:18432
	ds_read_b128 v[174:177], v238 offset:19456
	ds_read_b128 v[178:181], v238 offset:20480
	ds_read_b128 v[182:185], v238 offset:21504
	ds_read_b128 v[198:201], v238 offset:22528
	ds_read_b128 v[202:205], v238 offset:23552
	global_load_lds_dwordx4 v188, s[66:67]
	s_add_i32 m0, s47, 0x2000
	s_add_u32 s100, s66, s69
	s_addc_u32 s101, s67, 0
	s_add_i32 s1, s1, s57
	global_load_lds_dwordx4 v192, s[66:67]
	s_mov_b32 m0, s1
	s_nop 0
	global_load_lds_dwordx4 v188, s[100:101]
	s_add_i32 m0, s1, 0x2000
	s_nop 0
	global_load_lds_dwordx4 v192, s[100:101]
	s_mov_b32 m0, s90
	s_nop 0
	global_load_lds_dwordx4 v186, s[34:35]
	s_mov_b32 m0, s60
	s_nop 0
	global_load_lds_dwordx4 v190, s[34:35]
	s_waitcnt vmcnt(8)
	s_waitcnt lgkmcnt(0)
	s_barrier
	s_setprio 1
	s_waitcnt lgkmcnt(0)
	v_mfma_f32_16x16x32_bf16 v[62:65], v[130:133], v[162:165], v[62:65]
	v_mfma_f32_16x16x32_bf16 v[58:61], v[138:141], v[162:165], v[58:61]
	v_mfma_f32_16x16x32_bf16 v[46:49], v[130:133], v[170:173], v[46:49]
	v_mfma_f32_16x16x32_bf16 v[42:45], v[138:141], v[170:173], v[42:45]
	v_mfma_f32_16x16x32_bf16 v[30:33], v[130:133], v[178:181], v[30:33]
	v_mfma_f32_16x16x32_bf16 v[26:29], v[138:141], v[178:181], v[26:29]
	v_mfma_f32_16x16x32_bf16 v[14:17], v[130:133], v[198:201], v[14:17]
	v_mfma_f32_16x16x32_bf16 v[10:13], v[138:141], v[198:201], v[10:13]
	v_mfma_f32_16x16x32_bf16 v[62:65], v[134:137], v[166:169], v[62:65]
	v_mfma_f32_16x16x32_bf16 v[58:61], v[142:145], v[166:169], v[58:61]
	v_mfma_f32_16x16x32_bf16 v[46:49], v[134:137], v[174:177], v[46:49]
	v_mfma_f32_16x16x32_bf16 v[42:45], v[142:145], v[174:177], v[42:45]
	v_mfma_f32_16x16x32_bf16 v[30:33], v[134:137], v[182:185], v[30:33]
	v_mfma_f32_16x16x32_bf16 v[26:29], v[142:145], v[182:185], v[26:29]
	v_mfma_f32_16x16x32_bf16 v[14:17], v[134:137], v[202:205], v[14:17]
	v_mfma_f32_16x16x32_bf16 v[10:13], v[142:145], v[202:205], v[10:13]
	s_setprio 0
	s_setprio 1
	v_mfma_f32_16x16x32_bf16 v[54:57], v[146:149], v[162:165], v[54:57]
	v_mfma_f32_16x16x32_bf16 v[50:53], v[154:157], v[162:165], v[50:53]
	v_mfma_f32_16x16x32_bf16 v[38:41], v[146:149], v[170:173], v[38:41]
	v_mfma_f32_16x16x32_bf16 v[34:37], v[154:157], v[170:173], v[34:37]
	v_mfma_f32_16x16x32_bf16 v[22:25], v[146:149], v[178:181], v[22:25]
	v_mfma_f32_16x16x32_bf16 v[18:21], v[154:157], v[178:181], v[18:21]
	v_mfma_f32_16x16x32_bf16 v[6:9], v[146:149], v[198:201], v[6:9]
	v_mfma_f32_16x16x32_bf16 v[2:5], v[154:157], v[198:201], v[2:5]
	v_mfma_f32_16x16x32_bf16 v[54:57], v[150:153], v[166:169], v[54:57]
	v_mfma_f32_16x16x32_bf16 v[50:53], v[158:161], v[166:169], v[50:53]
	v_mfma_f32_16x16x32_bf16 v[38:41], v[150:153], v[174:177], v[38:41]
	v_mfma_f32_16x16x32_bf16 v[34:37], v[158:161], v[174:177], v[34:37]
	v_mfma_f32_16x16x32_bf16 v[22:25], v[150:153], v[182:185], v[22:25]
	v_mfma_f32_16x16x32_bf16 v[18:21], v[158:161], v[182:185], v[18:21]
	v_mfma_f32_16x16x32_bf16 v[6:9], v[150:153], v[202:205], v[6:9]
	v_mfma_f32_16x16x32_bf16 v[2:5], v[158:161], v[202:205], v[2:5]
	s_setprio 0
	s_barrier
	s_add_i32 s1, 0, 0x18000
	s_add_i32 s47, 0, 0x1c000
	ds_read_b128 v[130:133], v208
	ds_read_b128 v[134:137], v208 offset:1024
	ds_read_b128 v[138:141], v208 offset:2048
	ds_read_b128 v[142:145], v208 offset:3072
	ds_read_b128 v[146:149], v209
	ds_read_b128 v[150:153], v209 offset:1024
	ds_read_b128 v[154:157], v209 offset:2048
	ds_read_b128 v[158:161], v209 offset:3072
	s_mov_b32 m0, s61
	ds_read_b128 v[162:165], v238 offset:32768
	ds_read_b128 v[166:169], v238 offset:33792
	ds_read_b128 v[170:173], v238 offset:34816
	ds_read_b128 v[174:177], v238 offset:35840
	ds_read_b128 v[178:181], v238 offset:36864
	ds_read_b128 v[182:185], v238 offset:37888
	ds_read_b128 v[198:201], v238 offset:38912
	ds_read_b128 v[202:205], v238 offset:39936
	global_load_lds_dwordx4 v194, s[34:35]
	s_mov_b32 m0, s71
	s_nop 0
	global_load_lds_dwordx4 v196, s[34:35]
	s_waitcnt vmcnt(8)
	s_waitcnt lgkmcnt(0)
	s_barrier
	s_setprio 1
	s_waitcnt lgkmcnt(0)
	v_mfma_f32_16x16x32_bf16 v[126:129], v[130:133], v[162:165], v[126:129]
	v_mfma_f32_16x16x32_bf16 v[122:125], v[138:141], v[162:165], v[122:125]
	v_mfma_f32_16x16x32_bf16 v[118:121], v[130:133], v[170:173], v[118:121]
	v_mfma_f32_16x16x32_bf16 v[102:105], v[138:141], v[170:173], v[102:105]
	v_mfma_f32_16x16x32_bf16 v[94:97], v[130:133], v[178:181], v[94:97]
	v_mfma_f32_16x16x32_bf16 v[90:93], v[138:141], v[178:181], v[90:93]
	v_mfma_f32_16x16x32_bf16 v[78:81], v[130:133], v[198:201], v[78:81]
	v_mfma_f32_16x16x32_bf16 v[74:77], v[138:141], v[198:201], v[74:77]
	v_mfma_f32_16x16x32_bf16 v[126:129], v[134:137], v[166:169], v[126:129]
	v_mfma_f32_16x16x32_bf16 v[122:125], v[142:145], v[166:169], v[122:125]
	v_mfma_f32_16x16x32_bf16 v[118:121], v[134:137], v[174:177], v[118:121]
	v_mfma_f32_16x16x32_bf16 v[102:105], v[142:145], v[174:177], v[102:105]
	v_mfma_f32_16x16x32_bf16 v[94:97], v[134:137], v[182:185], v[94:97]
	v_mfma_f32_16x16x32_bf16 v[90:93], v[142:145], v[182:185], v[90:93]
	v_mfma_f32_16x16x32_bf16 v[78:81], v[134:137], v[202:205], v[78:81]
	v_mfma_f32_16x16x32_bf16 v[74:77], v[142:145], v[202:205], v[74:77]
	s_setprio 0
	s_setprio 1
	v_mfma_f32_16x16x32_bf16 v[114:117], v[146:149], v[162:165], v[114:117]
	v_mfma_f32_16x16x32_bf16 v[110:113], v[154:157], v[162:165], v[110:113]
	v_mfma_f32_16x16x32_bf16 v[106:109], v[146:149], v[170:173], v[106:109]
	v_mfma_f32_16x16x32_bf16 v[98:101], v[154:157], v[170:173], v[98:101]
	v_mfma_f32_16x16x32_bf16 v[86:89], v[146:149], v[178:181], v[86:89]
	v_mfma_f32_16x16x32_bf16 v[82:85], v[154:157], v[178:181], v[82:85]
	v_mfma_f32_16x16x32_bf16 v[70:73], v[146:149], v[198:201], v[70:73]
	v_mfma_f32_16x16x32_bf16 v[66:69], v[154:157], v[198:201], v[66:69]
	v_mfma_f32_16x16x32_bf16 v[114:117], v[150:153], v[166:169], v[114:117]
	v_mfma_f32_16x16x32_bf16 v[110:113], v[158:161], v[166:169], v[110:113]
	v_mfma_f32_16x16x32_bf16 v[106:109], v[150:153], v[174:177], v[106:109]
	v_mfma_f32_16x16x32_bf16 v[98:101], v[158:161], v[174:177], v[98:101]
	v_mfma_f32_16x16x32_bf16 v[86:89], v[150:153], v[182:185], v[86:89]
	v_mfma_f32_16x16x32_bf16 v[82:85], v[158:161], v[182:185], v[82:85]
	v_mfma_f32_16x16x32_bf16 v[70:73], v[150:153], v[202:205], v[70:73]
	v_mfma_f32_16x16x32_bf16 v[66:69], v[158:161], v[202:205], v[66:69]
	s_setprio 0
	s_barrier
	s_add_i32 s1, s1, s57
	s_add_u32 s66, s66, 0x80
	s_addc_u32 s67, s67, 0
	s_add_u32 s100, s100, 0x80
	s_addc_u32 s101, s101, 0
	s_add_u32 s34, s34, 0x80
	s_addc_u32 s35, s35, 0
	s_mov_b32 m0, s1
	ds_read_b128 v[162:165], v238 offset:49152
	ds_read_b128 v[166:169], v238 offset:50176
	ds_read_b128 v[170:173], v238 offset:51200
	ds_read_b128 v[174:177], v238 offset:52224
	ds_read_b128 v[178:181], v238 offset:53248
	ds_read_b128 v[182:185], v238 offset:54272
	ds_read_b128 v[198:201], v238 offset:55296
	ds_read_b128 v[202:205], v238 offset:56320
	global_load_lds_dwordx4 v188, s[66:67]
	s_add_i32 m0, s1, 0x2000
	s_add_i32 s1, s47, s57
	global_load_lds_dwordx4 v192, s[66:67]
	s_mov_b32 m0, s1
	s_nop 0
	global_load_lds_dwordx4 v188, s[100:101]
	s_add_i32 m0, s1, 0x2000
	s_nop 0
	global_load_lds_dwordx4 v192, s[100:101]
	s_mov_b32 m0, s64
	s_nop 0
	global_load_lds_dwordx4 v186, s[34:35]
	s_mov_b32 m0, s65
	s_nop 0
	global_load_lds_dwordx4 v190, s[34:35]
	s_waitcnt vmcnt(8)
	s_waitcnt lgkmcnt(0)
	s_barrier
	s_setprio 1
	s_waitcnt lgkmcnt(0)
	v_mfma_f32_16x16x32_bf16 v[62:65], v[130:133], v[162:165], v[62:65]
	v_mfma_f32_16x16x32_bf16 v[58:61], v[138:141], v[162:165], v[58:61]
	v_mfma_f32_16x16x32_bf16 v[46:49], v[130:133], v[170:173], v[46:49]
	v_mfma_f32_16x16x32_bf16 v[42:45], v[138:141], v[170:173], v[42:45]
	v_mfma_f32_16x16x32_bf16 v[30:33], v[130:133], v[178:181], v[30:33]
	v_mfma_f32_16x16x32_bf16 v[26:29], v[138:141], v[178:181], v[26:29]
	v_mfma_f32_16x16x32_bf16 v[14:17], v[130:133], v[198:201], v[14:17]
	v_mfma_f32_16x16x32_bf16 v[10:13], v[138:141], v[198:201], v[10:13]
	v_mfma_f32_16x16x32_bf16 v[62:65], v[134:137], v[166:169], v[62:65]
	v_mfma_f32_16x16x32_bf16 v[58:61], v[142:145], v[166:169], v[58:61]
	v_mfma_f32_16x16x32_bf16 v[46:49], v[134:137], v[174:177], v[46:49]
	v_mfma_f32_16x16x32_bf16 v[42:45], v[142:145], v[174:177], v[42:45]
	v_mfma_f32_16x16x32_bf16 v[30:33], v[134:137], v[182:185], v[30:33]
	v_mfma_f32_16x16x32_bf16 v[26:29], v[142:145], v[182:185], v[26:29]
	v_mfma_f32_16x16x32_bf16 v[14:17], v[134:137], v[202:205], v[14:17]
	v_mfma_f32_16x16x32_bf16 v[10:13], v[142:145], v[202:205], v[10:13]
	s_setprio 0
	s_setprio 1
	v_mfma_f32_16x16x32_bf16 v[54:57], v[146:149], v[162:165], v[54:57]
	v_mfma_f32_16x16x32_bf16 v[50:53], v[154:157], v[162:165], v[50:53]
	v_mfma_f32_16x16x32_bf16 v[38:41], v[146:149], v[170:173], v[38:41]
	v_mfma_f32_16x16x32_bf16 v[34:37], v[154:157], v[170:173], v[34:37]
	v_mfma_f32_16x16x32_bf16 v[22:25], v[146:149], v[178:181], v[22:25]
	v_mfma_f32_16x16x32_bf16 v[18:21], v[154:157], v[178:181], v[18:21]
	v_mfma_f32_16x16x32_bf16 v[6:9], v[146:149], v[198:201], v[6:9]
	v_mfma_f32_16x16x32_bf16 v[2:5], v[154:157], v[198:201], v[2:5]
	v_mfma_f32_16x16x32_bf16 v[54:57], v[150:153], v[166:169], v[54:57]
	v_mfma_f32_16x16x32_bf16 v[50:53], v[158:161], v[166:169], v[50:53]
	v_mfma_f32_16x16x32_bf16 v[38:41], v[150:153], v[174:177], v[38:41]
	v_mfma_f32_16x16x32_bf16 v[34:37], v[158:161], v[174:177], v[34:37]
	v_mfma_f32_16x16x32_bf16 v[22:25], v[150:153], v[182:185], v[22:25]
	v_mfma_f32_16x16x32_bf16 v[18:21], v[158:161], v[182:185], v[18:21]
	v_mfma_f32_16x16x32_bf16 v[6:9], v[150:153], v[202:205], v[6:9]
	v_mfma_f32_16x16x32_bf16 v[2:5], v[158:161], v[202:205], v[2:5]
	s_setprio 0
	s_barrier
	s_add_u32 s80, s80, 0x100
	s_addc_u32 s81, s81, 0
	s_add_u32 vcc_lo, vcc_lo, 0x100
	s_addc_u32 vcc_hi, vcc_hi, 0
	s_cmp_ge_u32 s0, s91
	s_mov_b32 s34, s0
	s_cbranch_scc0 .LBB0_169
	v_readlane_b32 s0, v243, 28
	v_readlane_b32 s1, v243, 29
	s_and_b64 vcc, exec, s[0:1]
	s_cbranch_vccz .LBB0_174
	s_barrier
	v_lshl_add_u32 v198, s99, 8, v1
	s_cmp_lt_i32 s70, 1
	s_mov_b64 s[34:35], -1
	s_cbranch_scc0 .LBB0_175
